# A2: attention X section: LDS read demand smoothed over the MFMA groups (head = 8 K reads only; V0 reads 4+4 behind QK^T groups 0/1); on top of BE1
# baseline (speedup 1.0000x reference)
.LBB0_633:
	s_waitcnt lgkmcnt(0)
	s_barrier
	v_lshl_add_u32 v187, s53, 14, v173
	s_lshl_b32 s52, s49, 14
	v_add_u32_e32 v208, s52, v174
	v_add_u32_e32 v209, s52, v175
	v_add_u32_e32 v210, s52, v176
	v_add_u32_e32 v211, s52, v177
	ds_read_b128 v[68:71], v208 offset:0
	ds_read_b128 v[72:75], v208 offset:0x2000
	ds_read_b128 v[204:207], v209 offset:0
	ds_read_b128 v[216:219], v209 offset:0x2000
	ds_read_b128 v[220:223], v210 offset:0
	ds_read_b128 v[224:227], v210 offset:0x2000
	ds_read_b128 v[228:231], v211 offset:0
	ds_read_b128 v[232:235], v211 offset:0x2000
	s_waitcnt lgkmcnt(4)
	v_mfma_f32_32x32x16_bf16 v[84:99], v[68:71], v[128:131], 0
	v_mfma_f32_32x32x16_bf16 v[68:83], v[72:75], v[128:131], 0
	v_mfma_f32_32x32x16_bf16 v[84:99], v[204:207], v[124:127], v[84:99]
	v_mfma_f32_32x32x16_bf16 v[68:83], v[216:219], v[124:127], v[68:83]
	ds_read_b64_tr_b16 v[188:189], v187 offset:0
	ds_read_b64_tr_b16 v[190:191], v187 offset:0x800
	ds_read_b64_tr_b16 v[192:193], v187 offset:0x1000
	ds_read_b64_tr_b16 v[194:195], v187 offset:0x1800
	ds_read_b128 v[204:207], v208 offset:0x80
	ds_read_b128 v[216:219], v208 offset:0x2080
	ds_read_b128 v[236:239], v209 offset:0x80
	ds_read_b128 v[242:245], v209 offset:0x2080
	s_waitcnt lgkmcnt(8)
	v_mfma_f32_32x32x16_bf16 v[84:99], v[220:223], v[120:123], v[84:99]
	v_mfma_f32_32x32x16_bf16 v[68:83], v[224:227], v[120:123], v[68:83]
	v_mfma_f32_32x32x16_bf16 v[84:99], v[228:231], v[116:119], v[84:99]
	v_mfma_f32_32x32x16_bf16 v[68:83], v[232:235], v[116:119], v[68:83]
	ds_read_b64_tr_b16 v[196:197], v187 offset:0x2000
	ds_read_b64_tr_b16 v[198:199], v187 offset:0x2800
	ds_read_b64_tr_b16 v[200:201], v187 offset:0x3000
	ds_read_b64_tr_b16 v[202:203], v187 offset:0x3800
	ds_read_b128 v[220:223], v210 offset:0x80
	ds_read_b128 v[224:227], v210 offset:0x2080
	ds_read_b128 v[228:231], v211 offset:0x80
	ds_read_b128 v[232:235], v211 offset:0x2080
	s_waitcnt lgkmcnt(8)
	v_mfma_f32_32x32x16_bf16 v[84:99], v[204:207], v[112:115], v[84:99]
	v_mfma_f32_32x32x16_bf16 v[68:83], v[216:219], v[112:115], v[68:83]
	v_mfma_f32_32x32x16_bf16 v[84:99], v[236:239], v[108:111], v[84:99]
	v_mfma_f32_32x32x16_bf16 v[68:83], v[242:245], v[108:111], v[68:83]
	s_waitcnt lgkmcnt(0)
	v_mfma_f32_32x32x16_bf16 v[84:99], v[220:223], v[104:107], v[84:99]
	v_mfma_f32_32x32x16_bf16 v[68:83], v[224:227], v[104:107], v[68:83]
	v_mfma_f32_32x32x16_bf16 v[84:99], v[228:231], v[100:103], v[84:99]
	v_mfma_f32_32x32x16_bf16 v[68:83], v[232:235], v[100:103], v[68:83]
	ds_read_b64_tr_b16 v[204:205], v187 offset:0x200
	ds_read_b64_tr_b16 v[206:207], v187 offset:0xa00
	ds_read_b64_tr_b16 v[216:217], v187 offset:0x1200
	ds_read_b64_tr_b16 v[218:219], v187 offset:0x1a00
	ds_read_b64_tr_b16 v[220:221], v187 offset:0x2200
	ds_read_b64_tr_b16 v[222:223], v187 offset:0x2a00
	ds_read_b64_tr_b16 v[224:225], v187 offset:0x3200
	ds_read_b64_tr_b16 v[226:227], v187 offset:0x3a00
	s_waitcnt lgkmcnt(8)
	v_mfma_f32_32x32x16_bf16 v[4:19], v[148:151], v[188:191], v[4:19]
	s_lshl_b32 s19, s51, 14
	s_add_i32 s8, s19, 0
	v_add_u32_e32 v236, s8, v179
	s_waitcnt vmcnt(0)
	v_mfma_f32_32x32x16_bf16 v[4:19], v[152:155], v[192:195], v[4:19]
	ds_write_b128 v236, v[144:147]
	v_add_u32_e32 v236, s8, v178
	v_mfma_f32_32x32x16_bf16 v[4:19], v[156:159], v[196:199], v[4:19]
	ds_write_b128 v236, v[136:139]
	v_add_u32_e32 v236, s8, v180
	v_mfma_f32_32x32x16_bf16 v[4:19], v[160:163], v[200:203], v[4:19]
	ds_read_b64_tr_b16 v[188:189], v187 offset:0x400
	ds_read_b64_tr_b16 v[190:191], v187 offset:0xc00
	ds_read_b64_tr_b16 v[192:193], v187 offset:0x1400
	ds_read_b64_tr_b16 v[194:195], v187 offset:0x1c00
	ds_read_b64_tr_b16 v[196:197], v187 offset:0x2400
	ds_read_b64_tr_b16 v[198:199], v187 offset:0x2c00
	ds_read_b64_tr_b16 v[200:201], v187 offset:0x3400
	ds_read_b64_tr_b16 v[202:203], v187 offset:0x3c00
	s_waitcnt lgkmcnt(10)
	v_mfma_f32_32x32x16_bf16 v[52:67], v[148:151], v[204:207], v[52:67]
	ds_write_b128 v236, v[140:143] offset:49152
	v_add_u32_e32 v236, s8, v181
	v_mfma_f32_32x32x16_bf16 v[52:67], v[152:155], v[216:219], v[52:67]
	ds_write_b128 v236, v[132:135] offset:49152
	s_add_i32 s48, s48, 1
	v_mfma_f32_32x32x16_bf16 v[52:67], v[156:159], v[220:223], v[52:67]
	s_sub_i32 s8, s50, s47
	s_min_u32 s36, s50, s8
	s_lshl_b64 s[8:9], s[36:37], 10
	s_cmp_lt_u32 s50, s47
	s_cselect_b32 s16, s30, s20
	s_cselect_b32 s17, s31, s21
	v_mfma_f32_32x32x16_bf16 v[52:67], v[160:163], v[224:227], v[52:67]
	ds_read_b64_tr_b16 v[204:205], v187 offset:0x600
	ds_read_b64_tr_b16 v[206:207], v187 offset:0xe00
	ds_read_b64_tr_b16 v[216:217], v187 offset:0x1600
	ds_read_b64_tr_b16 v[218:219], v187 offset:0x1e00
	ds_read_b64_tr_b16 v[220:221], v187 offset:0x2600
	ds_read_b64_tr_b16 v[222:223], v187 offset:0x2e00
	ds_read_b64_tr_b16 v[224:225], v187 offset:0x3600
	ds_read_b64_tr_b16 v[226:227], v187 offset:0x3e00
	s_waitcnt lgkmcnt(10)
	v_mfma_f32_32x32x16_bf16 v[36:51], v[148:151], v[188:191], v[36:51]
	s_cselect_b32 s36, s42, s26
	s_cselect_b32 s54, s43, s27
	s_add_u32 s16, s16, s8
	s_addc_u32 s17, s17, s9
	s_add_u32 s8, s36, s8
	s_addc_u32 s9, s54, s9
	v_mfma_f32_32x32x16_bf16 v[36:51], v[152:155], v[192:195], v[36:51]
	global_load_dwordx4 v[144:147], v2, s[8:9]
	s_add_u32 s8, s8, 0x8000
	s_addc_u32 s9, s9, 0
	v_mfma_f32_32x32x16_bf16 v[36:51], v[156:159], v[196:199], v[36:51]
	global_load_dwordx4 v[136:139], v2, s[8:9]
	global_load_dwordx4 v[140:143], v2, s[16:17]
	v_mfma_f32_32x32x16_bf16 v[36:51], v[160:163], v[200:203], v[36:51]
	s_add_u32 s16, s16, 0x8000
	s_addc_u32 s17, s17, 0
	global_load_dwordx4 v[132:135], v2, s[16:17]
	s_waitcnt lgkmcnt(0)
	v_mfma_f32_32x32x16_bf16 v[20:35], v[148:151], v[204:207], v[20:35]
	v_mfma_f32_32x32x16_bf16 v[20:35], v[152:155], v[216:219], v[20:35]
	v_mfma_f32_32x32x16_bf16 v[20:35], v[156:159], v[220:223], v[20:35]
	v_mfma_f32_32x32x16_bf16 v[20:35], v[160:163], v[224:227], v[20:35]
